# instruction selection: removed the identity adds (0 + e) at the head of the four attention stage bodies
# speedup vs baseline: 1.0023x; 1.0004x over previous
.LBB0_178:
	v_exp_f32_e32 v68, v80
	v_exp_f32_e32 v69, v81
	v_exp_f32_e32 v72, v82
	v_exp_f32_e32 v73, v83
	v_cvt_pk_bf16_f32 v176, v68, v69
	ds_read_b128 v[180:183], v220 offset:19968
	ds_read_b128 v[64:67], v220 offset:13312
	ds_read_b128 v[184:187], v220 offset:13344
	v_cvt_pk_bf16_f32 v177, v72, v73
	v_add_f32_e32 v68, v72, v68
	v_add_f32_e32 v69, v73, v69
	v_exp_f32_e32 v70, v84
	v_exp_f32_e32 v71, v85
	s_nop 0
	v_add_f32_e32 v68, v70, v68
	v_add_f32_e32 v69, v71, v69
	v_cvt_pk_bf16_f32 v178, v70, v71
	s_waitcnt lgkmcnt(1)
	v_mfma_f32_32x32x16_bf16 v[96:111], v[64:67], v[120:123], v[32:47]
	v_exp_f32_e32 v70, v86
	v_exp_f32_e32 v71, v87
	ds_read_b128 v[80:83], v220 offset:20000
	v_add_f32_e32 v188, v70, v68
	v_add_f32_e32 v189, v71, v69
	v_cvt_pk_bf16_f32 v179, v70, v71
	v_mfma_f32_32x32x16_bf16 v[64:79], v[180:183], v[120:123], v[32:47]
	v_exp_f32_e32 v89, v89
	v_exp_f32_e32 v88, v88
	ds_read_b128 v[84:87], v220 offset:13376
	v_add_f32_e32 v182, v89, v189
	v_add_f32_e32 v181, v88, v188
	v_cvt_pk_bf16_f32 v180, v88, v89
	s_waitcnt lgkmcnt(2)
	v_mfma_f32_32x32x16_bf16 v[96:111], v[184:187], v[124:127], v[96:111]
	ds_read_b128 v[188:191], v220 offset:20032
	v_exp_f32_e32 v88, v91
	v_exp_f32_e32 v89, v90
	v_add_f32_e32 v182, v88, v182
	v_add_f32_e32 v183, v89, v181
	v_cvt_pk_bf16_f32 v181, v89, v88
	s_waitcnt lgkmcnt(2)
	v_mfma_f32_32x32x16_bf16 v[64:79], v[80:83], v[124:127], v[64:79]
	v_exp_f32_e32 v80, v93
	v_exp_f32_e32 v81, v92
	ds_read_b128 v[88:91], v220 offset:13408
	v_add_f32_e32 v93, v80, v182
	v_add_f32_e32 v92, v81, v183
	v_cvt_pk_bf16_f32 v182, v81, v80
	s_waitcnt lgkmcnt(2)
	v_mfma_f32_32x32x16_bf16 v[96:111], v[84:87], v[128:131], v[96:111]
	v_exp_f32_e32 v94, v94
	v_exp_f32_e32 v95, v95
	ds_read_b128 v[80:83], v220 offset:20064
	v_add_f32_e32 v92, v94, v92
	v_add_f32_e32 v93, v95, v93
	v_cvt_pk_bf16_f32 v183, v94, v95
	s_waitcnt lgkmcnt(2)
	v_mfma_f32_32x32x16_bf16 v[64:79], v[188:191], v[128:131], v[64:79]
	v_exp_f32_e32 v49, v49
	v_exp_f32_e32 v48, v48
	ds_read_b128 v[84:87], v220 offset:13440
	v_add_f32_e32 v186, v49, v93
	v_add_f32_e32 v185, v48, v92
	v_cvt_pk_bf16_f32 v184, v48, v49
	s_waitcnt lgkmcnt(2)
	v_mfma_f32_32x32x16_bf16 v[96:111], v[88:91], v[132:135], v[96:111]
	v_exp_f32_e32 v48, v51
	v_exp_f32_e32 v49, v50
	ds_read_b128 v[92:95], v220 offset:20096
	v_add_f32_e32 v89, v48, v186
	v_add_f32_e32 v88, v49, v185
	v_cvt_pk_bf16_f32 v185, v49, v48
	s_waitcnt lgkmcnt(2)
	v_mfma_f32_32x32x16_bf16 v[64:79], v[80:83], v[132:135], v[64:79]
	ds_read_b128 v[48:51], v220 offset:13472
	v_exp_f32_e32 v53, v53
	v_exp_f32_e32 v52, v52
	v_add_f32_e32 v89, v53, v89
	v_add_f32_e32 v88, v52, v88
	v_cvt_pk_bf16_f32 v186, v52, v53
	s_waitcnt lgkmcnt(2)
	v_mfma_f32_32x32x16_bf16 v[96:111], v[84:87], v[136:139], v[96:111]
	v_exp_f32_e32 v52, v55
	v_exp_f32_e32 v53, v54
	ds_read_b128 v[80:83], v220 offset:20128
	v_add_f32_e32 v55, v52, v89
	v_add_f32_e32 v54, v53, v88
	v_cvt_pk_bf16_f32 v187, v53, v52
	s_waitcnt lgkmcnt(2)
	v_mfma_f32_32x32x16_bf16 v[64:79], v[92:95], v[136:139], v[64:79]
	v_exp_f32_e32 v52, v57
	v_exp_f32_e32 v53, v56
	ds_read_b128 v[84:87], v221 offset:35840
	v_add_f32_e32 v55, v52, v55
	v_add_f32_e32 v54, v53, v54
	v_cvt_pk_bf16_f32 v188, v53, v52
	s_waitcnt lgkmcnt(2)
	v_mfma_f32_32x32x16_bf16 v[96:111], v[48:51], v[140:143], v[96:111]
	v_exp_f32_e32 v48, v59
	v_exp_f32_e32 v49, v58
	ds_read_b128 v[88:91], v221 offset:40448
	v_add_f32_e32 v51, v48, v55
	v_add_f32_e32 v50, v49, v54
	v_cvt_pk_bf16_f32 v189, v49, v48
	s_waitcnt lgkmcnt(2)
	v_mfma_f32_32x32x16_bf16 v[64:79], v[80:83], v[140:143], v[64:79]
	ds_read_b128 v[52:55], v221 offset:35872
	v_exp_f32_e32 v48, v61
	v_exp_f32_e32 v49, v60
	v_add_f32_e32 v51, v48, v51
	v_add_f32_e32 v50, v49, v50
	v_cvt_pk_bf16_f32 v190, v49, v48
	s_waitcnt lgkmcnt(2)
	v_mfma_f32_32x32x16_bf16 v[0:15], v[84:87], v[164:167], v[0:15]
	v_exp_f32_e32 v48, v62
	v_exp_f32_e32 v49, v63
	ds_read_b128 v[60:63], v221 offset:40480
	v_add_f32_e32 v223, v48, v50
	v_add_f32_e32 v233, v49, v51
	v_cvt_pk_bf16_f32 v191, v48, v49
	s_waitcnt lgkmcnt(2)
	v_mfma_f32_32x32x16_bf16 v[16:31], v[88:91], v[164:167], v[16:31]
	ds_read_b128 v[48:51], v221 offset:35904
	s_waitcnt vmcnt(2)
	ds_write_b128 v197, v[148:151]
	s_and_saveexec_b64 s[44:45], s[8:9]
	ds_write_b128 v217, v[112:115]
	s_or_b64 exec, exec, s[44:45]
	s_add_i32 s29, s29, 2
	s_min_u32 s2, s29, 27
	s_mul_i32 s2, s2, 0x18000
	s_add_u32 s2, s80, s2
	s_addc_u32 s24, s81, 0
	s_add_u32 s44, s2, 0x60000
	s_addc_u32 s45, s24, 0
	v_lshl_add_u64 v[80:81], s[44:45], 0, v[202:203]
	s_waitcnt lgkmcnt(3)
	v_mfma_f32_32x32x16_bf16 v[0:15], v[52:55], v[160:163], v[0:15]
	ds_read_b128 v[56:59], v221 offset:40512
	v_max3_f32 v52, v96, s96, v64
	v_max3_f32 v52, v52, v97, v65
	v_max3_f32 v82, v52, v98, v66
	ds_write_b128 v219, v[144:147] offset:26624
	s_waitcnt lgkmcnt(4)
	v_mfma_f32_32x32x16_bf16 v[16:31], v[60:63], v[160:163], v[16:31]
	v_max3_f32 v60, v82, v99, v67
	v_max3_f32 v60, v60, v100, v68
	v_max3_f32 v60, v60, v101, v69
	ds_read_b128 v[52:55], v221 offset:35936
	global_load_dwordx4 v[148:151], v[80:81], off
	s_and_saveexec_b64 s[46:47], s[8:9]
	s_cbranch_execz .LBB0_182
	v_lshl_add_u64 v[62:63], s[44:45], 0, v[204:205]
	global_load_dwordx4 v[112:115], v[62:63], off

.LBB0_187:
	v_exp_f32_e32 v52, v96
	v_exp_f32_e32 v53, v97
	v_exp_f32_e32 v56, v98
	v_exp_f32_e32 v57, v99
	v_cvt_pk_bf16_f32 v164, v52, v53
	ds_read_b128 v[160:163], v220 offset:6656
	ds_read_b128 v[48:51], v220
	ds_read_b128 v[168:171], v220 offset:32
	v_cvt_pk_bf16_f32 v165, v56, v57
	v_add_f32_e32 v52, v56, v52
	v_add_f32_e32 v53, v57, v53
	v_exp_f32_e32 v54, v100
	v_exp_f32_e32 v55, v101
	s_nop 0
	v_add_f32_e32 v52, v54, v52
	v_add_f32_e32 v53, v55, v53
	v_cvt_pk_bf16_f32 v166, v54, v55
	s_waitcnt lgkmcnt(1)
	v_mfma_f32_32x32x16_bf16 v[80:95], v[48:51], v[120:123], v[32:47]
	v_exp_f32_e32 v54, v102
	v_exp_f32_e32 v55, v103
	ds_read_b128 v[96:99], v220 offset:6688
	v_add_f32_e32 v172, v54, v52
	v_add_f32_e32 v173, v55, v53
	v_cvt_pk_bf16_f32 v167, v54, v55
	v_mfma_f32_32x32x16_bf16 v[48:63], v[160:163], v[120:123], v[32:47]
	v_exp_f32_e32 v105, v105
	v_exp_f32_e32 v104, v104
	ds_read_b128 v[100:103], v220 offset:64
	v_add_f32_e32 v162, v105, v173
	v_add_f32_e32 v161, v104, v172
	v_cvt_pk_bf16_f32 v160, v104, v105
	s_waitcnt lgkmcnt(2)
	v_mfma_f32_32x32x16_bf16 v[80:95], v[168:171], v[124:127], v[80:95]
	ds_read_b128 v[172:175], v220 offset:6720
	v_exp_f32_e32 v104, v107
	v_exp_f32_e32 v105, v106
	v_add_f32_e32 v162, v104, v162
	v_add_f32_e32 v163, v105, v161
	v_cvt_pk_bf16_f32 v161, v105, v104
	s_waitcnt lgkmcnt(2)
	v_mfma_f32_32x32x16_bf16 v[48:63], v[96:99], v[124:127], v[48:63]
	v_exp_f32_e32 v96, v109
	v_exp_f32_e32 v97, v108
	ds_read_b128 v[104:107], v220 offset:96
	v_add_f32_e32 v109, v96, v162
	v_add_f32_e32 v108, v97, v163
	v_cvt_pk_bf16_f32 v162, v97, v96
	s_waitcnt lgkmcnt(2)
	v_mfma_f32_32x32x16_bf16 v[80:95], v[100:103], v[128:131], v[80:95]
	v_exp_f32_e32 v110, v110
	v_exp_f32_e32 v111, v111
	ds_read_b128 v[96:99], v220 offset:6752
	v_add_f32_e32 v108, v110, v108
	v_add_f32_e32 v109, v111, v109
	v_cvt_pk_bf16_f32 v163, v110, v111
	s_waitcnt lgkmcnt(2)
	v_mfma_f32_32x32x16_bf16 v[48:63], v[172:175], v[128:131], v[48:63]
	v_exp_f32_e32 v65, v65
	v_exp_f32_e32 v64, v64
	ds_read_b128 v[100:103], v220 offset:128
	v_add_f32_e32 v169, v65, v109
	v_add_f32_e32 v168, v64, v108
	v_cvt_pk_bf16_f32 v172, v64, v65
	s_waitcnt lgkmcnt(2)
	v_mfma_f32_32x32x16_bf16 v[80:95], v[104:107], v[132:135], v[80:95]
	v_exp_f32_e32 v64, v67
	v_exp_f32_e32 v65, v66
	ds_read_b128 v[108:111], v220 offset:6784
	v_add_f32_e32 v105, v64, v169
	v_add_f32_e32 v104, v65, v168
	v_cvt_pk_bf16_f32 v173, v65, v64
	s_waitcnt lgkmcnt(2)
	v_mfma_f32_32x32x16_bf16 v[48:63], v[96:99], v[132:135], v[48:63]
	ds_read_b128 v[64:67], v220 offset:160
	v_exp_f32_e32 v69, v69
	v_exp_f32_e32 v68, v68
	v_add_f32_e32 v105, v69, v105
	v_add_f32_e32 v104, v68, v104
	v_cvt_pk_bf16_f32 v174, v68, v69
	s_waitcnt lgkmcnt(2)
	v_mfma_f32_32x32x16_bf16 v[80:95], v[100:103], v[136:139], v[80:95]
	ds_read_b128 v[96:99], v220 offset:6816
	v_exp_f32_e32 v68, v71
	v_exp_f32_e32 v69, v70
	v_add_f32_e32 v71, v68, v105
	v_add_f32_e32 v70, v69, v104
	v_cvt_pk_bf16_f32 v175, v69, v68
	s_waitcnt lgkmcnt(2)
	v_mfma_f32_32x32x16_bf16 v[48:63], v[108:111], v[136:139], v[48:63]
	v_exp_f32_e32 v68, v73
	v_exp_f32_e32 v69, v72
	ds_read_b128 v[100:103], v221 offset:26624
	v_add_f32_e32 v71, v68, v71
	v_add_f32_e32 v70, v69, v70
	v_cvt_pk_bf16_f32 v168, v69, v68
	s_waitcnt lgkmcnt(2)
	v_mfma_f32_32x32x16_bf16 v[80:95], v[64:67], v[140:143], v[80:95]
	v_exp_f32_e32 v64, v75
	v_exp_f32_e32 v65, v74
	ds_read_b128 v[104:107], v221 offset:31232
	v_add_f32_e32 v67, v64, v71
	v_add_f32_e32 v66, v65, v70
	v_cvt_pk_bf16_f32 v169, v65, v64
	s_waitcnt lgkmcnt(2)
	v_mfma_f32_32x32x16_bf16 v[48:63], v[96:99], v[140:143], v[48:63]
	ds_read_b128 v[68:71], v221 offset:26656
	v_exp_f32_e32 v64, v77
	v_exp_f32_e32 v65, v76
	v_add_f32_e32 v67, v64, v67
	v_add_f32_e32 v66, v65, v66
	v_cvt_pk_bf16_f32 v170, v65, v64
	s_waitcnt lgkmcnt(2)
	v_mfma_f32_32x32x16_bf16 v[0:15], v[100:103], v[176:179], v[0:15]
	v_exp_f32_e32 v64, v78
	v_exp_f32_e32 v65, v79
	ds_read_b128 v[76:79], v221 offset:31264
	v_add_f32_e32 v96, v64, v66
	v_add_f32_e32 v97, v65, v67
	v_cvt_pk_bf16_f32 v171, v64, v65
	s_waitcnt lgkmcnt(2)
	v_mfma_f32_32x32x16_bf16 v[16:31], v[104:107], v[176:179], v[16:31]
	ds_read_b128 v[64:67], v221 offset:26688
	s_waitcnt vmcnt(2)
	ds_write_b128 v197, v[152:155] offset:13312
	s_and_saveexec_b64 s[44:45], s[8:9]
	ds_write_b128 v217, v[116:119] offset:13312
	s_or_b64 exec, exec, s[44:45]
	s_min_u32 s2, s29, 26
	s_mul_i32 s2, s2, 0x18000
	s_add_u32 s2, s80, s2
	s_addc_u32 s24, s81, 0
	s_add_u32 s44, s2, 0x78000
	s_addc_u32 s45, s24, 0
	v_lshl_add_u64 v[98:99], s[44:45], 0, v[202:203]
	s_waitcnt lgkmcnt(3)
	v_mfma_f32_32x32x16_bf16 v[0:15], v[68:71], v[180:183], v[0:15]
	ds_read_b128 v[72:75], v221 offset:31296
	v_max3_f32 v68, v80, s96, v48
	v_max3_f32 v68, v68, v81, v49
	v_max3_f32 v100, v68, v82, v50
	ds_write_b128 v219, v[156:159] offset:35840
	s_waitcnt lgkmcnt(4)
	v_mfma_f32_32x32x16_bf16 v[16:31], v[76:79], v[180:183], v[16:31]
	v_max3_f32 v76, v100, v83, v51
	v_max3_f32 v76, v76, v84, v52
	v_max3_f32 v76, v76, v85, v53
	ds_read_b128 v[68:71], v221 offset:26720
	global_load_dwordx4 v[152:155], v[98:99], off
	s_and_saveexec_b64 s[46:47], s[8:9]
	s_cbranch_execz .LBB0_191
	v_lshl_add_u64 v[78:79], s[44:45], 0, v[204:205]
	global_load_dwordx4 v[116:119], v[78:79], off

.LBB0_208:
	v_exp_f32_e32 v68, v80
	v_exp_f32_e32 v69, v81
	v_exp_f32_e32 v72, v82
	v_exp_f32_e32 v73, v83
	v_cvt_pk_bf16_f32 v164, v68, v69
	ds_read_b128 v[160:163], v197 offset:13824
	ds_read_b128 v[64:67], v197 offset:9216
	ds_read_b128 v[168:171], v197 offset:9248
	v_cvt_pk_bf16_f32 v165, v72, v73
	v_add_f32_e32 v68, v72, v68
	v_add_f32_e32 v69, v73, v69
	v_exp_f32_e32 v70, v84
	v_exp_f32_e32 v71, v85
	s_add_i32 s8, s8, 2
	v_add_f32_e32 v68, v70, v68
	v_add_f32_e32 v69, v71, v69
	v_cvt_pk_bf16_f32 v166, v70, v71
	s_waitcnt lgkmcnt(1)
	v_mfma_f32_32x32x16_bf16 v[96:111], v[64:67], v[124:127], v[32:47]
	ds_read_b128 v[172:175], v197 offset:13856
	v_exp_f32_e32 v70, v87
	v_exp_f32_e32 v71, v86
	s_min_u32 s2, s8, 27
	s_min_u32 s28, s8, 29
	s_lshl_b32 s2, s2, 14
	s_add_u32 s24, s10, s2
	s_addc_u32 s25, s11, 0
	s_lshl_b32 s40, s28, 7
	v_add_f32_e32 v190, v71, v68
	v_add_f32_e32 v202, v70, v69
	v_cvt_pk_bf16_f32 v167, v71, v70
	v_lshl_add_u64 v[80:81], s[24:25], 0, v[178:179]
	v_lshl_add_u64 v[82:83], v[186:187], 0, s[40:41]
	v_mfma_f32_32x32x16_bf16 v[64:79], v[160:163], v[124:127], v[32:47]
	v_exp_f32_e32 v89, v89
	v_exp_f32_e32 v88, v88
	ds_read_b128 v[84:87], v197 offset:9280
	v_add_f32_e32 v162, v89, v202
	v_add_f32_e32 v161, v88, v190
	v_cvt_pk_bf16_f32 v160, v88, v89
	s_waitcnt lgkmcnt(2)
	v_mfma_f32_32x32x16_bf16 v[96:111], v[168:171], v[116:119], v[96:111]
	ds_read_b128 v[202:205], v197 offset:13888
	v_exp_f32_e32 v88, v91
	v_exp_f32_e32 v89, v90
	v_add_f32_e32 v162, v88, v162
	v_add_f32_e32 v163, v89, v161
	v_cvt_pk_bf16_f32 v161, v89, v88
	s_waitcnt lgkmcnt(2)
	v_mfma_f32_32x32x16_bf16 v[64:79], v[172:175], v[116:119], v[64:79]
	v_exp_f32_e32 v93, v93
	v_exp_f32_e32 v92, v92
	ds_read_b128 v[88:91], v197 offset:9312
	v_add_f32_e32 v168, v93, v162
	v_add_f32_e32 v163, v92, v163
	v_cvt_pk_bf16_f32 v162, v92, v93
	s_waitcnt lgkmcnt(2)
	v_mfma_f32_32x32x16_bf16 v[96:111], v[84:87], v[112:115], v[96:111]
	v_exp_f32_e32 v169, v94
	v_exp_f32_e32 v170, v95
	ds_read_b128 v[92:95], v197 offset:13920
	v_add_f32_e32 v171, v169, v163
	v_add_f32_e32 v168, v170, v168
	v_cvt_pk_bf16_f32 v163, v169, v170
	s_waitcnt lgkmcnt(2)
	v_mfma_f32_32x32x16_bf16 v[64:79], v[202:205], v[112:115], v[64:79]
	v_exp_f32_e32 v49, v49
	v_exp_f32_e32 v48, v48
	ds_read_b128 v[84:87], v200 offset:27648
	v_add_f32_e32 v170, v49, v168
	v_add_f32_e32 v169, v48, v171
	v_cvt_pk_bf16_f32 v168, v48, v49
	s_waitcnt lgkmcnt(2)
	v_mfma_f32_32x32x16_bf16 v[96:111], v[88:91], v[120:123], v[96:111]
	ds_read_b128 v[172:175], v200 offset:32256
	v_exp_f32_e32 v48, v51
	v_exp_f32_e32 v49, v50
	v_add_f32_e32 v89, v48, v170
	v_add_f32_e32 v88, v49, v169
	v_cvt_pk_bf16_f32 v169, v49, v48
	s_waitcnt lgkmcnt(2)
	v_mfma_f32_32x32x16_bf16 v[64:79], v[92:95], v[120:123], v[64:79]
	ds_read_b128 v[48:51], v200 offset:27680
	v_exp_f32_e32 v53, v53
	v_exp_f32_e32 v52, v52
	v_add_f32_e32 v93, v53, v89
	v_add_f32_e32 v92, v52, v88
	v_cvt_pk_bf16_f32 v170, v52, v53
	s_waitcnt lgkmcnt(2)
	v_mfma_f32_32x32x16_bf16 v[0:15], v[84:87], v[152:155], v[0:15]
	v_exp_f32_e32 v52, v55
	v_exp_f32_e32 v53, v54
	ds_read_b128 v[88:91], v200 offset:32288
	v_add_f32_e32 v85, v52, v93
	v_add_f32_e32 v84, v53, v92
	v_cvt_pk_bf16_f32 v171, v53, v52
	s_waitcnt lgkmcnt(2)
	v_mfma_f32_32x32x16_bf16 v[16:31], v[172:175], v[152:155], v[16:31]
	v_exp_f32_e32 v57, v57
	v_exp_f32_e32 v56, v56
	ds_read_b128 v[52:55], v200 offset:27712
	v_add_f32_e32 v93, v57, v85
	v_add_f32_e32 v92, v56, v84
	v_cvt_pk_bf16_f32 v172, v56, v57
	s_waitcnt lgkmcnt(2)
	v_mfma_f32_32x32x16_bf16 v[0:15], v[48:51], v[144:147], v[0:15]
	v_exp_f32_e32 v48, v59
	v_exp_f32_e32 v49, v58
	ds_read_b128 v[84:87], v200 offset:32320
	v_add_f32_e32 v57, v48, v93
	v_cvt_pk_bf16_f32 v173, v49, v48
	v_max3_f32 v48, v96, s96, v64
	v_max3_f32 v48, v48, v97, v65
	v_add_f32_e32 v56, v49, v92
	v_max3_f32 v58, v48, v98, v66
	s_waitcnt lgkmcnt(2)
	v_mfma_f32_32x32x16_bf16 v[16:31], v[88:91], v[144:147], v[16:31]
	v_exp_f32_e32 v60, v60
	ds_read_b128 v[48:51], v200 offset:27744
	v_exp_f32_e32 v59, v61
	v_add_f32_e32 v61, v60, v56
	v_max3_f32 v56, v58, v99, v67
	v_max3_f32 v56, v56, v100, v68
	v_add_f32_e32 v88, v59, v57
	v_cvt_pk_bf16_f32 v174, v60, v59
	v_max3_f32 v60, v56, v101, v69
	s_waitcnt lgkmcnt(2)
	v_mfma_f32_32x32x16_bf16 v[0:15], v[52:55], v[156:159], v[0:15]
	v_exp_f32_e32 v62, v62
	v_exp_f32_e32 v63, v63
	ds_read_b128 v[56:59], v200 offset:32352
	v_max3_f32 v52, v60, v102, v70
	v_max3_f32 v52, v52, v103, v71
	v_add_f32_e32 v202, v62, v61
	v_add_f32_e32 v203, v63, v88
	v_cvt_pk_bf16_f32 v175, v62, v63
	v_max3_f32 v52, v52, v104, v72
	s_waitcnt lgkmcnt(2)
	v_mfma_f32_32x32x16_bf16 v[16:31], v[84:87], v[156:159], v[16:31]
	v_max3_f32 v52, v52, v105, v73
	v_max3_f32 v52, v52, v106, v74
	v_max3_f32 v52, v52, v107, v75
	s_waitcnt vmcnt(2)
	ds_write_b128 v189, v[136:139]
	s_waitcnt lgkmcnt(2)
	v_mfma_f32_32x32x16_bf16 v[0:15], v[48:51], v[148:151], v[0:15]
	v_max3_f32 v48, v52, v108, v76
	v_max3_f32 v48, v48, v109, v77
	v_max3_f32 v48, v48, v110, v78
	ds_write_b128 v191, v[128:131] offset:18432
	v_add_co_u32_e32 v50, vcc, 0x10000, v80
	v_max3_f32 v48, v48, v111, v79
	s_nop 0
	v_addc_co_u32_e32 v51, vcc, 0, v81, vcc
	global_load_dwordx4 v[136:139], v[50:51], off
	global_load_dwordx4 v[128:131], v[82:83], off offset:256
	s_waitcnt lgkmcnt(2)
	v_mfma_f32_32x32x16_bf16 v[16:31], v[56:59], v[148:151], v[16:31]
	s_waitcnt lgkmcnt(0)
	s_barrier
	s_and_b64 vcc, exec, s[12:13]
	s_cbranch_vccz .LBB0_210
	v_pk_mul_f32 v[14:15], v[188:189], v[14:15] op_sel_hi:[0,1]
	v_pk_mul_f32 v[12:13], v[188:189], v[12:13] op_sel_hi:[0,1]
	v_pk_mul_f32 v[10:11], v[188:189], v[10:11] op_sel_hi:[0,1]
	v_pk_mul_f32 v[8:9], v[188:189], v[8:9] op_sel_hi:[0,1]
	v_pk_mul_f32 v[6:7], v[188:189], v[6:7] op_sel_hi:[0,1]
	v_pk_mul_f32 v[4:5], v[188:189], v[4:5] op_sel_hi:[0,1]
	v_pk_mul_f32 v[2:3], v[188:189], v[2:3] op_sel_hi:[0,1]
	v_pk_mul_f32 v[0:1], v[188:189], v[0:1] op_sel_hi:[0,1]
	s_nop 1
	v_pk_mul_f32 v[30:31], v[188:189], v[30:31] op_sel_hi:[0,1]
	v_pk_mul_f32 v[28:29], v[188:189], v[28:29] op_sel_hi:[0,1]
	v_pk_mul_f32 v[26:27], v[188:189], v[26:27] op_sel_hi:[0,1]
	v_pk_mul_f32 v[24:25], v[188:189], v[24:25] op_sel_hi:[0,1]
	v_pk_mul_f32 v[22:23], v[188:189], v[22:23] op_sel_hi:[0,1]
	v_pk_mul_f32 v[20:21], v[188:189], v[20:21] op_sel_hi:[0,1]
	v_pk_mul_f32 v[18:19], v[188:189], v[18:19] op_sel_hi:[0,1]
	v_pk_mul_f32 v[16:17], v[188:189], v[16:17] op_sel_hi:[0,1]

.LBB0_213:
	v_exp_f32_e32 v52, v96
	v_exp_f32_e32 v53, v97
	v_exp_f32_e32 v56, v98
	v_exp_f32_e32 v57, v99
	v_cvt_pk_bf16_f32 v152, v52, v53
	ds_read_b128 v[144:147], v197 offset:4608
	ds_read_b128 v[48:51], v197
	ds_read_b128 v[148:151], v197 offset:32
	v_cvt_pk_bf16_f32 v153, v56, v57
	v_add_f32_e32 v52, v56, v52
	v_add_f32_e32 v53, v57, v53
	v_exp_f32_e32 v54, v100
	v_exp_f32_e32 v55, v101
	s_nop 0
	v_add_f32_e32 v52, v54, v52
	v_add_f32_e32 v53, v55, v53
	v_cvt_pk_bf16_f32 v154, v54, v55
	s_waitcnt lgkmcnt(1)
	v_mfma_f32_32x32x16_bf16 v[80:95], v[48:51], v[124:127], v[32:47]
	ds_read_b128 v[156:159], v197 offset:4640
	v_exp_f32_e32 v54, v103
	v_exp_f32_e32 v55, v102
	s_min_u32 s2, s8, 26
	s_min_u32 s28, s8, 28
	s_lshl_b32 s2, s2, 14
	s_add_u32 s24, s10, s2
	s_addc_u32 s25, s11, 0
	s_lshl_b32 s40, s28, 7
	v_add_f32_e32 v204, v55, v52
	v_add_f32_e32 v205, v54, v53
	v_cvt_pk_bf16_f32 v155, v55, v54
	v_lshl_add_u64 v[96:97], s[24:25], 0, v[178:179]
	v_lshl_add_u64 v[98:99], v[186:187], 0, s[40:41]
	v_mfma_f32_32x32x16_bf16 v[48:63], v[144:147], v[124:127], v[32:47]
	v_exp_f32_e32 v105, v105
	v_exp_f32_e32 v104, v104
	ds_read_b128 v[100:103], v197 offset:64
	v_add_f32_e32 v146, v105, v205
	v_add_f32_e32 v145, v104, v204
	v_cvt_pk_bf16_f32 v144, v104, v105
	s_waitcnt lgkmcnt(2)
	v_mfma_f32_32x32x16_bf16 v[80:95], v[148:151], v[116:119], v[80:95]
	v_exp_f32_e32 v104, v107
	v_exp_f32_e32 v105, v106
	ds_read_b128 v[204:207], v197 offset:4672
	v_add_f32_e32 v146, v104, v146
	v_add_f32_e32 v147, v105, v145
	v_cvt_pk_bf16_f32 v145, v105, v104
	s_waitcnt lgkmcnt(2)
	v_mfma_f32_32x32x16_bf16 v[48:63], v[156:159], v[116:119], v[48:63]
	v_exp_f32_e32 v109, v109
	v_exp_f32_e32 v108, v108
	ds_read_b128 v[104:107], v197 offset:96
	v_add_f32_e32 v148, v109, v146
	v_add_f32_e32 v147, v108, v147
	v_cvt_pk_bf16_f32 v146, v108, v109
	s_waitcnt lgkmcnt(2)
	v_mfma_f32_32x32x16_bf16 v[80:95], v[100:103], v[112:115], v[80:95]
	v_exp_f32_e32 v149, v110
	v_exp_f32_e32 v150, v111
	ds_read_b128 v[108:111], v197 offset:4704
	v_add_f32_e32 v151, v149, v147
	v_add_f32_e32 v148, v150, v148
	v_cvt_pk_bf16_f32 v147, v149, v150
	s_waitcnt lgkmcnt(2)
	v_mfma_f32_32x32x16_bf16 v[48:63], v[204:207], v[112:115], v[48:63]
	v_exp_f32_e32 v65, v65
	v_exp_f32_e32 v64, v64
	ds_read_b128 v[100:103], v200 offset:18432
	v_add_f32_e32 v158, v65, v148
	v_add_f32_e32 v157, v64, v151
	v_cvt_pk_bf16_f32 v156, v64, v65
	s_waitcnt lgkmcnt(2)
	v_mfma_f32_32x32x16_bf16 v[80:95], v[104:107], v[120:123], v[80:95]
	ds_read_b128 v[148:151], v200 offset:23040
	v_exp_f32_e32 v64, v67
	v_exp_f32_e32 v65, v66
	v_add_f32_e32 v105, v64, v158
	v_add_f32_e32 v104, v65, v157
	v_cvt_pk_bf16_f32 v157, v65, v64
	s_waitcnt lgkmcnt(2)
	v_mfma_f32_32x32x16_bf16 v[48:63], v[108:111], v[120:123], v[48:63]
	ds_read_b128 v[64:67], v200 offset:18464
	v_exp_f32_e32 v69, v69
	v_exp_f32_e32 v68, v68
	v_add_f32_e32 v109, v69, v105
	v_add_f32_e32 v108, v68, v104
	v_cvt_pk_bf16_f32 v158, v68, v69
	s_waitcnt lgkmcnt(2)
	v_mfma_f32_32x32x16_bf16 v[0:15], v[100:103], v[164:167], v[0:15]
	v_exp_f32_e32 v68, v71
	v_exp_f32_e32 v69, v70
	ds_read_b128 v[104:107], v200 offset:23072
	v_add_f32_e32 v101, v68, v109
	v_add_f32_e32 v100, v69, v108
	v_cvt_pk_bf16_f32 v159, v69, v68
	s_waitcnt lgkmcnt(2)
	v_mfma_f32_32x32x16_bf16 v[16:31], v[148:151], v[164:167], v[16:31]
	v_exp_f32_e32 v73, v73
	v_exp_f32_e32 v72, v72
	ds_read_b128 v[68:71], v200 offset:18496
	v_add_f32_e32 v109, v73, v101
	v_add_f32_e32 v108, v72, v100
	v_cvt_pk_bf16_f32 v148, v72, v73
	s_waitcnt lgkmcnt(2)
	v_mfma_f32_32x32x16_bf16 v[0:15], v[64:67], v[160:163], v[0:15]
	v_exp_f32_e32 v64, v75
	v_exp_f32_e32 v65, v74
	ds_read_b128 v[100:103], v200 offset:23104
	v_add_f32_e32 v67, v64, v109
	v_cvt_pk_bf16_f32 v149, v65, v64
	v_max3_f32 v64, v80, s96, v48
	v_max3_f32 v64, v64, v81, v49
	v_add_f32_e32 v66, v65, v108
	v_max3_f32 v64, v64, v82, v50
	s_waitcnt lgkmcnt(2)
	v_mfma_f32_32x32x16_bf16 v[16:31], v[104:107], v[160:163], v[16:31]
	v_exp_f32_e32 v65, v77
	v_exp_f32_e32 v76, v76
	ds_read_b128 v[72:75], v200 offset:18528
	v_max3_f32 v64, v64, v83, v51
	v_max3_f32 v64, v64, v84, v52
	v_add_f32_e32 v66, v76, v66
	v_add_f32_e32 v67, v65, v67
	v_cvt_pk_bf16_f32 v150, v76, v65
	v_max3_f32 v104, v64, v85, v53
	s_waitcnt lgkmcnt(2)
	v_mfma_f32_32x32x16_bf16 v[0:15], v[68:71], v[168:171], v[0:15]
	v_exp_f32_e32 v105, v78
	v_exp_f32_e32 v106, v79
	ds_read_b128 v[76:79], v200 offset:23136
	v_add_f32_e32 v64, v105, v66
	v_max3_f32 v66, v104, v86, v54
	v_max3_f32 v66, v66, v87, v55
	v_add_f32_e32 v65, v106, v67
	v_cvt_pk_bf16_f32 v151, v105, v106
	v_max3_f32 v66, v66, v88, v56
	s_waitcnt lgkmcnt(2)
	v_mfma_f32_32x32x16_bf16 v[16:31], v[100:103], v[168:171], v[16:31]
	v_max3_f32 v66, v66, v89, v57
	v_max3_f32 v66, v66, v90, v58
	v_max3_f32 v66, v66, v91, v59
	s_waitcnt vmcnt(3)
	ds_write_b128 v189, v[140:143] offset:9216
	s_waitcnt lgkmcnt(2)
	v_mfma_f32_32x32x16_bf16 v[0:15], v[72:75], v[172:175], v[0:15]
	v_max3_f32 v66, v66, v92, v60
	v_max3_f32 v66, v66, v93, v61
	v_max3_f32 v66, v66, v94, v62
	s_waitcnt vmcnt(2)
	ds_write_b128 v191, v[132:135] offset:27648
	v_add_co_u32_e32 v68, vcc, 0x14000, v96
	v_max3_f32 v66, v66, v95, v63
	s_nop 0
	v_addc_co_u32_e32 v69, vcc, 0, v97, vcc
	global_load_dwordx4 v[140:143], v[68:69], off
	global_load_dwordx4 v[132:135], v[98:99], off offset:384
	s_waitcnt lgkmcnt(2)
	v_mfma_f32_32x32x16_bf16 v[16:31], v[76:79], v[172:175], v[16:31]
	s_waitcnt lgkmcnt(0)
	s_barrier
	s_andn2_b64 vcc, exec, s[12:13]
	s_cbranch_vccnz .LBB0_215
	v_pk_mul_f32 v[14:15], v[190:191], v[14:15] op_sel_hi:[0,1]
	v_pk_mul_f32 v[12:13], v[190:191], v[12:13] op_sel_hi:[0,1]
	v_pk_mul_f32 v[10:11], v[190:191], v[10:11] op_sel_hi:[0,1]
	v_pk_mul_f32 v[8:9], v[190:191], v[8:9] op_sel_hi:[0,1]
	v_pk_mul_f32 v[6:7], v[190:191], v[6:7] op_sel_hi:[0,1]
	v_pk_mul_f32 v[4:5], v[190:191], v[4:5] op_sel_hi:[0,1]
	v_pk_mul_f32 v[2:3], v[190:191], v[2:3] op_sel_hi:[0,1]
	v_pk_mul_f32 v[0:1], v[190:191], v[0:1] op_sel_hi:[0,1]
	s_nop 1
	v_pk_mul_f32 v[30:31], v[190:191], v[30:31] op_sel_hi:[0,1]
	v_pk_mul_f32 v[28:29], v[190:191], v[28:29] op_sel_hi:[0,1]
	v_pk_mul_f32 v[26:27], v[190:191], v[26:27] op_sel_hi:[0,1]
	v_pk_mul_f32 v[24:25], v[190:191], v[24:25] op_sel_hi:[0,1]
	v_pk_mul_f32 v[22:23], v[190:191], v[22:23] op_sel_hi:[0,1]
	v_pk_mul_f32 v[20:21], v[190:191], v[20:21] op_sel_hi:[0,1]
	v_pk_mul_f32 v[18:19], v[190:191], v[18:19] op_sel_hi:[0,1]
	v_pk_mul_f32 v[16:17], v[190:191], v[16:17] op_sel_hi:[0,1]
